# compress-tile code: packed f32 adds beside MFMAs split into scalar pairs (bit-identical), dependent-chain s_nops dropped
# baseline (speedup 1.0000x reference)
; DI void attn_tile(LAS const unsigned char* Ks, LAS const unsigned char* VT, const bf16x8 (&qf)[4], int ql, int hi,
;                   bool need_mask, bool col_en, int lo_b, int hi_b, float& m_ref, float& l_run, f32x16 (&o)[2], f32x16 (&sp)[2]) {
;     const int lane_ = ql + 32 * hi;
;     const float bias = col_en ? -m_ref : -INFINITY;
;     const bool plain = __all(col_en && (m_ref == 0.f));
; #pragma unroll
;     for (int p = 0; p < 2; ++p) {
;         bf16x8 kf[4];
; #pragma unroll
;         for (int d0 = 0; d0 < 4; ++d0) { const int c = 2 * d0 + hi; kf[d0] = *(LAS const bf16x8*)(Ks + c * 1024 + ((ql + 32 * p) << 4)); }
;         f32x16 acc;
;         if (plain) {
; #pragma unroll
;             for (int r = 0; r < 16; ++r) acc[r] = 0.f;
; #pragma unroll
;             for (int d0 = 0; d0 < 4; ++d0) acc = MFMA32(kf[d0], qf[d0], acc);
;         } else {
; #pragma unroll
;             for (int r = 0; r < 16; ++r) acc[r] = bias;
; #pragma unroll
;             for (int d0 = 0; d0 < 4; ++d0) acc = MFMA32(kf[d0], qf[d0], acc);
;         }
;         sp[p] = acc;
;     }
;     if (need_mask) {
; #pragma unroll
;         for (int p = 0; p < 2; ++p)
; #pragma unroll
;             for (int r = 0; r < 16; ++r) { const int kvl = 32 * p + (r & 3) + 8 * (r >> 2) + 4 * hi; const bool ok = (kvl <= hi_b) && (kvl > lo_b); sp[p][r] = ok ? sp[p][r] : -INFINITY; }
;     }
;     float tm = fmaxf(fmaxf(sp[0][0], sp[0][1]), sp[1][0]);
; #pragma unroll
;     for (int r = 2; r < 16; r += 2) tm = fmaxf(fmaxf(tm, sp[0][r]), sp[0][r + 1]);
; #pragma unroll
;     for (int r = 1; r < 15; r += 2) tm = fmaxf(fmaxf(tm, sp[1][r]), sp[1][r + 1]);
;     tm = fmaxf(tm, sp[1][15]);
;     tm = half_max(tm);
;     if (__any((tm > 16.f) || ((tm < -16.f) && (tm > -INFINITY)))) {
;         const bool up = tm > 16.f;
;         const bool dn = (tm < -16.f) && (tm > -INFINITY) && (half_sum(l_run) == 0.f);
;         const float dlt = (up || dn) ? tm : 0.f;
;         const float alpha = up ? fast_exp2(-dlt) : 1.0f;
;         l_run *= alpha; m_ref += dlt;
; #pragma unroll
;         for (int r = 0; r < 16; ++r) { o[0][r] *= alpha; o[1][r] *= alpha; sp[0][r] -= dlt; sp[1][r] -= dlt; }
; DI void attn_unit(LAS unsigned char* lds, const Args& a, int bg, int qt) {
;     ...
;     DMA_TILE(KC, KC + VC_OFF, 0);
;     if (two_cmp) DMA_TILE(KC + 4096, KC + VC_OFF + 4096, 1);
;     DMA_TILE(KS, KS + KV_SLOT, 2);
.LBB0_741:
	s_lshl_b64 s[8:9], s[8:9], 18
	s_add_u32 s54, s58, s8
	s_addc_u32 s55, s59, s9
	v_lshl_add_u64 v[2:3], s[54:55], 0, v[100:101]
	s_add_i32 s8, s78, 0x8000
	s_mov_b32 s9, m0
	s_mov_b32 m0, s8
	s_nop 0
	global_load_lds_dwordx4 v[2:3], off
	s_mov_b32 m0, s9
	v_lshl_add_u64 v[2:3], s[54:55], 0, v[150:151]
	v_lshl_add_u64 v[2:3], v[2:3], 0, s[50:51]
	s_add_i32 s8, s78, 0xa000
	s_mov_b32 s9, m0
	s_mov_b32 m0, s8
	s_nop 0
	global_load_lds_dwordx4 v[2:3], off
	s_mov_b32 m0, s9
	s_waitcnt vmcnt(0)
	ds_write2st64_b32 v133, v8, v9 offset1:8
	ds_write_b32 v133, v10 offset:4096
	s_waitcnt lgkmcnt(0)
	s_barrier
	ds_read_b128 v[2:5], v236
	ds_read_b128 v[6:9], v236 offset:512
	s_waitcnt vmcnt(3) lgkmcnt(1)
	v_mfma_f32_32x32x16_bf16 v[18:33], v[2:5], v[66:69], 0
	ds_read_b128 v[34:37], v236 offset:2048
	ds_read_b128 v[38:41], v236 offset:2560
	s_sub_i32 s8, s10, 31
	s_waitcnt vmcnt(2) lgkmcnt(1)
	v_mfma_f32_32x32x16_bf16 v[18:33], v[34:37], v[70:73], v[18:33]
	ds_read_b128 v[34:37], v236 offset:4096
	ds_read_b128 v[44:47], v236 offset:4608
	v_mfma_f32_32x32x16_bf16 v[2:17], v[6:9], v[66:69], 0
	s_waitcnt vmcnt(1) lgkmcnt(1)
	v_mfma_f32_32x32x16_bf16 v[18:33], v[34:37], v[74:77], v[18:33]
	ds_read_b128 v[34:37], v236 offset:6144
	ds_read_b128 v[48:51], v236 offset:6656
	s_waitcnt vmcnt(0) lgkmcnt(1)
	v_mfma_f32_32x32x16_bf16 v[18:33], v[34:37], v[78:81], v[18:33]
	v_add_u32_e32 v34, s8, v139
	v_ashrrev_i32_e32 v151, 4, v34
	v_cmp_le_i32_e32 vcc, v1, v151
	v_mfma_f32_32x32x16_bf16 v[2:17], v[38:41], v[70:73], v[2:17]
	s_nop 7
	v_cndmask_b32_e32 v43, v237, v18, vcc
	v_cmp_gt_i32_e32 vcc, v151, v1
	s_nop 1
	v_cndmask_b32_e32 v42, v237, v19, vcc
	v_cmp_le_i32_e32 vcc, v99, v151
	v_mfma_f32_32x32x16_bf16 v[2:17], v[44:47], v[74:77], v[2:17]
	s_nop 0
	v_cndmask_b32_e32 v41, v237, v21, vcc
	v_cmp_le_i32_e32 vcc, v104, v151
	s_nop 1
	v_cndmask_b32_e32 v40, v237, v20, vcc
	v_cmp_le_i32_e32 vcc, v103, v151
	s_waitcnt lgkmcnt(0)
	v_mfma_f32_32x32x16_bf16 v[2:17], v[48:51], v[78:81], v[2:17]
	v_cndmask_b32_e32 v39, v237, v23, vcc
	v_cmp_le_i32_e32 vcc, v106, v151
	s_nop 1
	v_cndmask_b32_e32 v38, v237, v22, vcc
	v_cmp_le_i32_e32 vcc, v105, v151
	s_nop 1
	v_cndmask_b32_e32 v37, v237, v25, vcc
	v_cmp_le_i32_e32 vcc, v108, v151
	s_nop 1
	v_cndmask_b32_e32 v36, v237, v24, vcc
	v_cmp_le_i32_e32 vcc, v107, v151
	s_nop 1
	v_cndmask_b32_e32 v25, v237, v27, vcc
	v_cmp_le_i32_e32 vcc, v110, v151
	s_nop 1
	v_cndmask_b32_e32 v24, v237, v26, vcc
	v_cmp_le_i32_e32 vcc, v109, v151
	s_nop 1
	v_cndmask_b32_e32 v23, v237, v29, vcc
	v_cmp_le_i32_e32 vcc, v112, v151
	s_nop 1
	v_cndmask_b32_e32 v22, v237, v28, vcc
	v_cmp_le_i32_e32 vcc, v111, v151
	s_nop 1
	v_cndmask_b32_e32 v21, v237, v31, vcc
	v_cmp_le_i32_e32 vcc, v114, v151
	s_nop 1
	v_cndmask_b32_e32 v20, v237, v30, vcc
	v_cmp_le_i32_e32 vcc, v113, v151
	s_nop 1
	v_cndmask_b32_e32 v19, v237, v33, vcc
	v_cmp_le_i32_e32 vcc, v116, v151
	s_nop 1
	v_cndmask_b32_e32 v18, v237, v32, vcc
	v_cmp_le_i32_e32 vcc, v115, v151
	s_nop 1
	v_cndmask_b32_e32 v31, v237, v3, vcc
	v_cmp_le_i32_e32 vcc, v118, v151
	s_nop 1
	v_cndmask_b32_e32 v35, v237, v2, vcc
	v_cmp_le_i32_e32 vcc, v117, v151
	s_nop 1
	v_cndmask_b32_e32 v30, v237, v5, vcc
	v_cmp_le_i32_e32 vcc, v120, v151
	s_nop 1
	v_cndmask_b32_e32 v33, v237, v4, vcc
	v_cmp_le_i32_e32 vcc, v119, v151
	s_nop 1
	v_cndmask_b32_e32 v5, v237, v7, vcc
	v_cmp_le_i32_e32 vcc, v122, v151
	s_nop 1
	v_cndmask_b32_e32 v32, v237, v6, vcc
	v_cmp_le_i32_e32 vcc, v121, v151
	s_nop 1
	v_cndmask_b32_e32 v4, v237, v9, vcc
	v_cmp_le_i32_e32 vcc, v124, v151
	v_max_f32_e32 v9, v42, v42
	s_nop 0
	v_cndmask_b32_e32 v8, v237, v8, vcc
	v_cmp_le_i32_e32 vcc, v123, v151
	s_nop 1
	v_cndmask_b32_e32 v3, v237, v11, vcc
	v_cmp_le_i32_e32 vcc, v126, v151
	s_nop 1
	v_cndmask_b32_e32 v7, v237, v10, vcc
	v_max_f32_e32 v10, v43, v43
	v_max_f32_e32 v9, v10, v9
	v_max3_f32 v9, v9, v35, v40
	v_max3_f32 v9, v9, v41, v38
	v_max3_f32 v9, v9, v39, v36
	v_max3_f32 v9, v9, v37, v24
	v_max3_f32 v9, v9, v25, v22
	v_max3_f32 v9, v9, v23, v20
	v_max3_f32 v9, v9, v21, v18
	v_cmp_le_i32_e32 vcc, v125, v151
	v_max3_f32 v9, v9, v19, v31
	v_max3_f32 v9, v9, v33, v30
	v_cndmask_b32_e32 v2, v237, v13, vcc
	v_cmp_le_i32_e32 vcc, v128, v151
	v_max3_f32 v9, v9, v32, v5
	v_max3_f32 v9, v9, v8, v4
	v_cndmask_b32_e32 v6, v237, v12, vcc
	v_cmp_le_i32_e32 vcc, v127, v151
	v_max3_f32 v9, v9, v7, v3
	v_max3_f32 v9, v9, v6, v2
	v_cndmask_b32_e32 v26, v237, v15, vcc
	v_cmp_le_i32_e32 vcc, v130, v151
	s_nop 1
	v_cndmask_b32_e32 v29, v237, v14, vcc
	v_cmp_le_i32_e32 vcc, v129, v151
	v_max3_f32 v9, v9, v29, v26
	s_nop 0
	v_cndmask_b32_e32 v27, v237, v17, vcc
	v_cmp_le_i32_e32 vcc, v132, v151
	s_nop 1
	v_cndmask_b32_e32 v28, v237, v16, vcc
	v_max3_f32 v9, v9, v28, v27
	v_mov_b32_e32 v10, v9
	s_nop 1
	v_permlane32_swap_b32_e32 v9, v10
	v_max_f32_e32 v10, v10, v10
	v_max_f32_e32 v9, v9, v9
	v_max_f32_e32 v9, v9, v10
	v_cmp_gt_f32_e32 vcc, s66, v9
	v_cmp_lg_f32_e64 s[10:11], s64, v9
	v_cmp_lt_f32_e64 s[8:9], s65, v9
	s_and_b64 s[20:21], vcc, s[10:11]
	s_or_b64 vcc, s[8:9], s[20:21]
	s_cbranch_vccz .LBB0_745
	s_mov_b64 s[10:11], 0
	s_and_saveexec_b64 s[18:19], s[20:21]
	v_mov_b32_e32 v10, v101
	v_mov_b32_e32 v11, v101
	s_nop 1
	v_permlane32_swap_b32_e32 v10, v11
	v_add_f32_e32 v10, v10, v11
	v_cmp_eq_f32_e32 vcc, 0, v10
	s_and_b64 s[10:11], vcc, exec
	s_or_b64 exec, exec, s[18:19]
	s_or_b64 vcc, s[8:9], s[10:11]
	v_cndmask_b32_e32 v10, 0, v9, vcc
	v_exp_f32_e64 v9, -v10
	v_add_f32_e32 v137, 0, v10
	v_sub_f32_e32 v42, v42, v10
	v_sub_f32_e32 v43, v43, v10
	v_sub_f32_e32 v40, v40, v10
	v_sub_f32_e32 v41, v41, v10
	v_mul_f32_e32 v9, 0, v9
	v_cndmask_b32_e64 v34, 0, v9, s[8:9]
	v_sub_f32_e32 v38, v38, v10
	v_sub_f32_e32 v39, v39, v10
	v_sub_f32_e32 v36, v36, v10
	v_sub_f32_e32 v37, v37, v10
	v_sub_f32_e32 v24, v24, v10
	v_sub_f32_e32 v25, v25, v10
	v_sub_f32_e32 v22, v22, v10
	v_sub_f32_e32 v23, v23, v10
	v_sub_f32_e32 v20, v20, v10
	v_sub_f32_e32 v21, v21, v10
	v_sub_f32_e32 v18, v18, v10
	v_sub_f32_e32 v19, v19, v10
	v_sub_f32_e32 v35, v35, v10
	v_sub_f32_e32 v31, v31, v10
	v_sub_f32_e32 v33, v33, v10
	v_sub_f32_e32 v30, v30, v10
	v_sub_f32_e32 v32, v32, v10
	v_sub_f32_e32 v5, v5, v10
	v_sub_f32_e32 v8, v8, v10
	v_sub_f32_e32 v4, v4, v10
	v_sub_f32_e32 v7, v7, v10
	v_sub_f32_e32 v3, v3, v10
	v_sub_f32_e32 v6, v6, v10
	v_sub_f32_e32 v2, v2, v10
	v_sub_f32_e32 v29, v29, v10
	v_sub_f32_e32 v26, v26, v10
	v_sub_f32_e32 v28, v28, v10
	v_sub_f32_e32 v27, v27, v10
	s_branch .LBB0_746

; #define LAS __attribute__((address_space(3)))
; DI float fast_exp2(float x) { return __builtin_amdgcn_exp2f(x); }
; #define MFMA32(a, b, c) __builtin_amdgcn_mfma_f32_32x32x16_bf16((a), (b), (c), 0, 0, 0)
; DI void attn_tile(LAS const unsigned char* Ks, LAS const unsigned char* VT, const bf16x8 (&qf)[4], int ql, int hi,
;                   bool need_mask, bool col_en, int lo_b, int hi_b, float& m_ref, float& l_run, f32x16 (&o)[2], f32x16 (&sp)[2]) {
;     const int lane_ = ql + 32 * hi;
;     const float bias = col_en ? -m_ref : -INFINITY;
;     const bool plain = __all(col_en && (m_ref == 0.f));
; #pragma unroll
;     for (int p = 0; p < 2; ++p) {
;         bf16x8 kf[4];
; #pragma unroll
;         for (int d0 = 0; d0 < 4; ++d0) { const int c = 2 * d0 + hi; kf[d0] = *(LAS const bf16x8*)(Ks + c * 1024 + ((ql + 32 * p) << 4)); }
;         f32x16 acc;
;         if (plain) {
; #pragma unroll
;             for (int r = 0; r < 16; ++r) acc[r] = 0.f;
; #pragma unroll
;             for (int d0 = 0; d0 < 4; ++d0) acc = MFMA32(kf[d0], qf[d0], acc);
;         } else {
; #pragma unroll
;             for (int r = 0; r < 16; ++r) acc[r] = bias;
; #pragma unroll
;             for (int d0 = 0; d0 < 4; ++d0) acc = MFMA32(kf[d0], qf[d0], acc);
;         }
;     ...
;     f32x2_t ps = {0.f, 0.f};
; #pragma unroll
;     for (int r = 0; r < 16; ++r) { const float e0 = fast_exp2(sp[0][r]), e1 = fast_exp2(sp[1][r]); sp[0][r] = e0; sp[1][r] = e1; ps += (f32x2_t){e0, e1}; }
;     l_run += ps[0] + ps[1];
.LBB0_748:
	v_add_f32_e32 v36, 0, v94
	v_add_f32_e32 v37, 0, v95
	s_and_b64 vcc, exec, s[8:9]
	v_add_f32_e32 v36, v92, v36
	v_add_f32_e32 v37, v93, v37
	s_mov_b64 s[10:11], 0
	v_add_f32_e32 v36, v90, v36
	v_add_f32_e32 v37, v91, v37
	v_add_f32_e32 v36, v88, v36
	v_add_f32_e32 v37, v89, v37
	v_add_f32_e32 v36, v86, v36
	v_add_f32_e32 v37, v87, v37
	v_add_f32_e32 v36, v84, v36
	v_add_f32_e32 v37, v85, v37
	v_add_f32_e32 v36, v82, v36
	v_add_f32_e32 v37, v83, v37
	v_add_f32_e32 v36, v64, v36
	v_add_f32_e32 v37, v65, v37
	v_add_f32_e32 v36, v62, v36
	v_add_f32_e32 v37, v63, v37
	v_add_f32_e32 v36, v60, v36
	v_add_f32_e32 v37, v61, v37
	v_add_f32_e32 v36, v58, v36
	v_add_f32_e32 v37, v59, v37
	v_add_f32_e32 v36, v56, v36
	v_add_f32_e32 v37, v57, v37
	v_add_f32_e32 v36, v54, v36
	v_add_f32_e32 v37, v55, v37
	v_add_f32_e32 v36, v52, v36
	v_add_f32_e32 v37, v53, v37
	v_add_f32_e32 v36, v50, v36
	v_add_f32_e32 v37, v51, v37
	v_add_f32_e32 v36, v96, v36
	v_add_f32_e32 v37, v97, v37
	v_add_f32_e32 v35, v36, v37
	v_add_f32_e32 v149, v34, v35
	s_cbranch_vccnz .LBB0_761
	ds_read_b128 v[94:97], v236 offset:16384
	ds_read_b128 v[90:93], v236 offset:18432
	ds_read_b128 v[86:89], v236 offset:20480
	ds_read_b128 v[82:85], v236 offset:22528
	v_cmp_eq_f32_e32 vcc, 0, v137
	s_cmp_lg_u64 vcc, exec
	s_cselect_b64 s[10:11], -1, 0
	s_cmp_eq_u64 vcc, exec
	s_mov_b64 s[12:13], -1
	v_xor_b32_e32 v34, 0x80000000, v137
	s_cbranch_scc1 .LBB0_751
	v_mov_b32_e32 v48, v34
	v_mov_b32_e32 v49, v34
	v_mov_b32_e32 v35, v34
	v_mov_b32_e32 v36, v34
	v_mov_b32_e32 v37, v34
	v_mov_b32_e32 v38, v34
	v_mov_b32_e32 v39, v34
	v_mov_b32_e32 v40, v34
	v_mov_b32_e32 v41, v34
	v_mov_b32_e32 v42, v34
	v_mov_b32_e32 v43, v34
	v_mov_b32_e32 v44, v34
	v_mov_b32_e32 v45, v34
	v_mov_b32_e32 v46, v34
	v_mov_b32_e32 v47, v34
	v_mov_b64_e32 v[64:65], v[48:49]
	v_mov_b64_e32 v[62:63], v[46:47]
	v_mov_b64_e32 v[60:61], v[44:45]
	v_mov_b64_e32 v[58:59], v[42:43]
	v_mov_b64_e32 v[56:57], v[40:41]
	v_mov_b64_e32 v[54:55], v[38:39]
	v_mov_b64_e32 v[52:53], v[36:37]
	v_mov_b64_e32 v[50:51], v[34:35]
	s_mov_b64 s[12:13], 0
	s_waitcnt lgkmcnt(3)
	v_mfma_f32_32x32x16_bf16 v[50:65], v[94:97], v[66:69], v[50:65]
	s_waitcnt lgkmcnt(2)
	v_mfma_f32_32x32x16_bf16 v[50:65], v[90:93], v[70:73], v[50:65]
	s_waitcnt lgkmcnt(1)
	v_mfma_f32_32x32x16_bf16 v[50:65], v[86:89], v[74:77], v[50:65]
	s_waitcnt lgkmcnt(0)
	v_mfma_f32_32x32x16_bf16 v[50:65], v[82:85], v[78:81], v[50:65]

; DI float fast_exp2(float x) { return __builtin_amdgcn_exp2f(x); }
; DI float half_max(float v) { auto rr = __builtin_amdgcn_permlane32_swap(__float_as_uint(v), __float_as_uint(v), false, false); return fmaxf(__uint_as_float(rr[0]), __uint_as_float(rr[1])); }
; DI float half_sum(float v) { auto rr = __builtin_amdgcn_permlane32_swap(__float_as_uint(v), __float_as_uint(v), false, false); return __uint_as_float(rr[0]) + __uint_as_float(rr[1]); }
; DI void attn_tile(LAS const unsigned char* Ks, LAS const unsigned char* VT, const bf16x8 (&qf)[4], int ql, int hi,
;                   bool need_mask, bool col_en, int lo_b, int hi_b, float& m_ref, float& l_run, f32x16 (&o)[2], f32x16 (&sp)[2]) {
;     ...
;     if (need_mask) {
; #pragma unroll
;         for (int p = 0; p < 2; ++p)
; #pragma unroll
;             for (int r = 0; r < 16; ++r) { const int kvl = 32 * p + (r & 3) + 8 * (r >> 2) + 4 * hi; const bool ok = (kvl <= hi_b) && (kvl > lo_b); sp[p][r] = ok ? sp[p][r] : -INFINITY; }
;     }
;     float tm = fmaxf(fmaxf(sp[0][0], sp[0][1]), sp[1][0]);
; #pragma unroll
;     for (int r = 2; r < 16; r += 2) tm = fmaxf(fmaxf(tm, sp[0][r]), sp[0][r + 1]);
; #pragma unroll
;     for (int r = 1; r < 15; r += 2) tm = fmaxf(fmaxf(tm, sp[1][r]), sp[1][r + 1]);
;     tm = fmaxf(tm, sp[1][15]);
;     tm = half_max(tm);
;     if (__any((tm > 16.f) || ((tm < -16.f) && (tm > -INFINITY)))) {
;         const bool up = tm > 16.f;
;         const bool dn = (tm < -16.f) && (tm > -INFINITY) && (half_sum(l_run) == 0.f);
;         const float dlt = (up || dn) ? tm : 0.f;
;         const float alpha = up ? fast_exp2(-dlt) : 1.0f;
;         l_run *= alpha; m_ref += dlt;
; #pragma unroll
;         for (int r = 0; r < 16; ++r) { o[0][r] *= alpha; o[1][r] *= alpha; sp[0][r] -= dlt; sp[1][r] -= dlt; }
;     }
.LBB0_757:
	s_waitcnt lgkmcnt(2)
	v_subrev_u32_e32 v90, 64, v151
	v_cmp_le_i32_e32 vcc, v1, v90
	s_waitcnt lgkmcnt(1)
	s_nop 0
	v_cndmask_b32_e32 v89, v237, v50, vcc
	v_cmp_gt_i32_e32 vcc, v90, v1
	s_nop 1
	v_cndmask_b32_e32 v88, v237, v51, vcc
	v_cmp_le_i32_e32 vcc, v99, v90
	s_nop 1
	v_cndmask_b32_e32 v87, v237, v53, vcc
	v_cmp_le_i32_e32 vcc, v104, v90
	s_nop 1
	v_cndmask_b32_e32 v86, v237, v52, vcc
	v_cmp_le_i32_e32 vcc, v103, v90
	s_waitcnt lgkmcnt(0)
	s_nop 0
	v_cndmask_b32_e32 v85, v237, v55, vcc
	v_cmp_le_i32_e32 vcc, v106, v90
	s_nop 1
	v_cndmask_b32_e32 v84, v237, v54, vcc
	v_cmp_le_i32_e32 vcc, v105, v90
	s_nop 1
	v_cndmask_b32_e32 v83, v237, v57, vcc
	v_cmp_le_i32_e32 vcc, v108, v90
	s_nop 1
	v_cndmask_b32_e32 v82, v237, v56, vcc
	v_cmp_le_i32_e32 vcc, v107, v90
	s_nop 1
	v_cndmask_b32_e32 v57, v237, v59, vcc
	v_cmp_le_i32_e32 vcc, v110, v90
	s_nop 1
	v_cndmask_b32_e32 v56, v237, v58, vcc
	v_cmp_le_i32_e32 vcc, v109, v90
	s_nop 1
	v_cndmask_b32_e32 v55, v237, v61, vcc
	v_cmp_le_i32_e32 vcc, v112, v90
	s_nop 1
	v_cndmask_b32_e32 v54, v237, v60, vcc
	v_cmp_le_i32_e32 vcc, v111, v90
	s_nop 1
	v_cndmask_b32_e32 v53, v237, v63, vcc
	v_cmp_le_i32_e32 vcc, v114, v90
	s_nop 1
	v_cndmask_b32_e32 v52, v237, v62, vcc
	v_cmp_le_i32_e32 vcc, v113, v90
	s_nop 1
	v_cndmask_b32_e32 v51, v237, v65, vcc
	v_cmp_le_i32_e32 vcc, v116, v90
	s_nop 1
	v_cndmask_b32_e32 v50, v237, v64, vcc
	v_cmp_le_i32_e32 vcc, v115, v90
	s_nop 1
	v_cndmask_b32_e32 v96, v237, v35, vcc
	v_cmp_le_i32_e32 vcc, v118, v90
	s_nop 1
	v_cndmask_b32_e32 v35, v237, v34, vcc
	v_cmp_le_i32_e32 vcc, v117, v90
	v_max_f32_e32 v34, v88, v88
	s_nop 0
	v_cndmask_b32_e32 v94, v237, v37, vcc
	v_cmp_le_i32_e32 vcc, v120, v90
	s_nop 1
	v_cndmask_b32_e32 v97, v237, v36, vcc
	v_max_f32_e32 v36, v89, v89
	v_max_f32_e32 v34, v36, v34
	v_max3_f32 v34, v34, v35, v86
	v_cmp_le_i32_e32 vcc, v119, v90
	v_max3_f32 v34, v34, v87, v84
	v_max3_f32 v34, v34, v85, v82
	v_cndmask_b32_e32 v58, v237, v39, vcc
	v_cmp_le_i32_e32 vcc, v122, v90
	v_max3_f32 v34, v34, v83, v56
	v_max3_f32 v34, v34, v57, v54
	v_cndmask_b32_e32 v95, v237, v38, vcc
	v_cmp_le_i32_e32 vcc, v121, v90
	v_max3_f32 v34, v34, v55, v52
	v_max3_f32 v34, v34, v53, v50
	v_cndmask_b32_e32 v59, v237, v41, vcc
	v_cmp_le_i32_e32 vcc, v124, v90
	v_max3_f32 v34, v34, v51, v96
	v_max3_f32 v34, v34, v97, v94
	v_cndmask_b32_e32 v93, v237, v40, vcc
	v_cmp_le_i32_e32 vcc, v123, v90
	v_max3_f32 v34, v34, v95, v58
	v_max3_f32 v34, v34, v93, v59
	v_cndmask_b32_e32 v60, v237, v43, vcc
	v_cmp_le_i32_e32 vcc, v126, v90
	s_nop 1
	v_cndmask_b32_e32 v62, v237, v42, vcc
	v_cmp_le_i32_e32 vcc, v125, v90
	v_max3_f32 v34, v34, v62, v60
	s_nop 0
	v_cndmask_b32_e32 v63, v237, v45, vcc
	v_cmp_le_i32_e32 vcc, v128, v90
	s_nop 1
	v_cndmask_b32_e32 v61, v237, v44, vcc
	v_cmp_le_i32_e32 vcc, v127, v90
	v_max3_f32 v34, v34, v61, v63
	s_nop 0
	v_cndmask_b32_e32 v91, v237, v47, vcc
	v_cmp_le_i32_e32 vcc, v130, v90
	s_nop 1
	v_cndmask_b32_e32 v92, v237, v46, vcc
	v_cmp_le_i32_e32 vcc, v129, v90
	v_max3_f32 v34, v34, v92, v91
	s_nop 0
	v_cndmask_b32_e32 v65, v237, v49, vcc
	v_cmp_le_i32_e32 vcc, v132, v90
	s_nop 1
	v_cndmask_b32_e32 v90, v237, v48, vcc
	v_max3_f32 v34, v34, v90, v65
	v_mov_b32_e32 v36, v34
	s_nop 1
	v_permlane32_swap_b32_e32 v34, v36
	v_max_f32_e32 v36, v36, v36
	v_max_f32_e32 v34, v34, v34
	v_max_f32_e32 v34, v34, v36
	v_cmp_gt_f32_e32 vcc, s66, v34
	v_cmp_lg_f32_e64 s[12:13], s64, v34
	v_cmp_lt_f32_e64 s[10:11], s65, v34
	s_and_b64 s[20:21], vcc, s[12:13]
	s_or_b64 vcc, s[10:11], s[20:21]
	s_cbranch_vccz .LBB0_762
	s_mov_b64 s[12:13], 0
	s_and_saveexec_b64 s[18:19], s[20:21]
	v_mov_b32_e32 v36, v149
	v_mov_b32_e32 v37, v149
	s_nop 1
	v_permlane32_swap_b32_e32 v36, v37
	v_add_f32_e32 v36, v36, v37
	v_cmp_eq_f32_e32 vcc, 0, v36
	s_and_b64 s[12:13], vcc, exec
	s_or_b64 exec, exec, s[18:19]
	s_or_b64 vcc, s[10:11], s[12:13]
	v_cndmask_b32_e32 v34, 0, v34, vcc
	v_exp_f32_e64 v36, -v34
	v_add_f32_e32 v64, v137, v34
	v_sub_f32_e32 v88, v88, v34
	v_sub_f32_e32 v89, v89, v34
	v_sub_f32_e32 v86, v86, v34
	v_sub_f32_e32 v87, v87, v34
	v_cndmask_b32_e64 v36, 1.0, v36, s[10:11]
	v_mul_f32_e32 v149, v149, v36
	v_sub_f32_e32 v84, v84, v34
	v_sub_f32_e32 v85, v85, v34
	v_sub_f32_e32 v82, v82, v34
	v_sub_f32_e32 v83, v83, v34
	v_sub_f32_e32 v56, v56, v34
	v_sub_f32_e32 v57, v57, v34
	v_sub_f32_e32 v54, v54, v34
	v_sub_f32_e32 v55, v55, v34
	v_sub_f32_e32 v52, v52, v34
	v_sub_f32_e32 v53, v53, v34
	v_pk_mul_f32 v[32:33], v[32:33], v[36:37] op_sel_hi:[1,0]
	v_pk_mul_f32 v[30:31], v[30:31], v[36:37] op_sel_hi:[1,0]
	v_pk_mul_f32 v[28:29], v[28:29], v[36:37] op_sel_hi:[1,0]
	v_pk_mul_f32 v[26:27], v[26:27], v[36:37] op_sel_hi:[1,0]
	v_pk_mul_f32 v[24:25], v[24:25], v[36:37] op_sel_hi:[1,0]
	v_pk_mul_f32 v[22:23], v[22:23], v[36:37] op_sel_hi:[1,0]
	v_pk_mul_f32 v[20:21], v[20:21], v[36:37] op_sel_hi:[1,0]
	v_pk_mul_f32 v[18:19], v[18:19], v[36:37] op_sel_hi:[1,0]
	v_pk_mul_f32 v[16:17], v[16:17], v[36:37] op_sel_hi:[1,0]
	v_pk_mul_f32 v[14:15], v[14:15], v[36:37] op_sel_hi:[1,0]
	v_pk_mul_f32 v[12:13], v[12:13], v[36:37] op_sel_hi:[1,0]
	v_pk_mul_f32 v[10:11], v[10:11], v[36:37] op_sel_hi:[1,0]
	v_pk_mul_f32 v[8:9], v[8:9], v[36:37] op_sel_hi:[1,0]
	v_pk_mul_f32 v[6:7], v[6:7], v[36:37] op_sel_hi:[1,0]
	v_pk_mul_f32 v[4:5], v[4:5], v[36:37] op_sel_hi:[1,0]
	v_pk_mul_f32 v[2:3], v[2:3], v[36:37] op_sel_hi:[1,0]
	v_sub_f32_e32 v50, v50, v34
	v_sub_f32_e32 v51, v51, v34
	v_sub_f32_e32 v35, v35, v34
	v_sub_f32_e32 v96, v96, v34
	v_sub_f32_e32 v97, v97, v34
	v_sub_f32_e32 v94, v94, v34
	v_sub_f32_e32 v95, v95, v34
	v_sub_f32_e32 v58, v58, v34
	v_sub_f32_e32 v93, v93, v34
	v_sub_f32_e32 v59, v59, v34
	v_sub_f32_e32 v62, v62, v34
	v_sub_f32_e32 v60, v60, v34
	v_sub_f32_e32 v61, v61, v34
	v_sub_f32_e32 v63, v63, v34
	v_sub_f32_e32 v92, v92, v34
	v_sub_f32_e32 v91, v91, v34
	v_sub_f32_e32 v90, v90, v34
	v_sub_f32_e32 v65, v65, v34
	s_branch .LBB0_763

; #define LAS __attribute__((address_space(3)))
; DI float fast_exp2(float x) { return __builtin_amdgcn_exp2f(x); }
; DI void attn_tile(LAS const unsigned char* Ks, LAS const unsigned char* VT, const bf16x8 (&qf)[4], int ql, int hi,
;                   bool need_mask, bool col_en, int lo_b, int hi_b, float& m_ref, float& l_run, f32x16 (&o)[2], f32x16 (&sp)[2]) {
;     ...
;     f32x2_t ps = {0.f, 0.f};
; #pragma unroll
;     for (int r = 0; r < 16; ++r) { const float e0 = fast_exp2(sp[0][r]), e1 = fast_exp2(sp[1][r]); sp[0][r] = e0; sp[1][r] = e1; ps += (f32x2_t){e0, e1}; }
;     l_run += ps[0] + ps[1];
;     bf16x8 pk[2][2];
; #pragma unroll
;     for (int p = 0; p < 2; ++p)
; #pragma unroll
;         for (int s = 0; s < 2; ++s) { u32x4 w; w.x = pk2(sp[p][8 * s], sp[p][8 * s + 1]); w.y = pk2(sp[p][8 * s + 2], sp[p][8 * s + 3]); w.z = pk2(sp[p][8 * s + 4], sp[p][8 * s + 5]); w.w = pk2(sp[p][8 * s + 6], sp[p][8 * s + 7]); pk[p][s] = __builtin_bit_cast(bf16x8, w); }
;     LAS const unsigned char* vb = VT + ((lane_ >> 4) & 1) * 32 + (lane_ & 3) * 8 + (4 * hi + ((lane_ & 15) >> 2)) * 64;
; #pragma unroll
;     for (int dh = 0; dh < 2; ++dh) {
;         bf16x8 vf[4];
; #pragma unroll
;         for (int ks = 0; ks < 4; ++ks) {
;             const s16x4 lo = __builtin_bit_cast(s16x4, __builtin_amdgcn_ds_read_tr16_b64_v4i16((LAS v4i16_t*)(vb + dh * 4096 + ks * 1024)));
;             const s16x4 hh = __builtin_bit_cast(s16x4, __builtin_amdgcn_ds_read_tr16_b64_v4i16((LAS v4i16_t*)(vb + dh * 4096 + ks * 1024 + 512)));
;             vf[ks] = (bf16x8){lo[0], lo[1], lo[2], lo[3], hh[0], hh[1], hh[2], hh[3]};
;         }
; #pragma unroll
;         for (int ks = 0; ks < 4; ++ks) o[dh] = MFMA32(vf[ks], pk[ks >> 1][ks & 1], o[dh]);
;     }
; }
; DI void attn_unit(LAS unsigned char* lds, const Args& a, int bg, int qt) {
;     ...
;             float prev = 0.f;
;             if (two_cmp)
; #pragma unroll
;             for (int kk = 0; kk < 8; ++kk) { const int p = kk >> 2, k = kk & 3;
;                 const float xk = __shfl_xor(sp[p][4 * k + 3], 32);
;                 const float e4 = (sp[p][4 * k] + sp[p][4 * k + 1]) + (sp[p][4 * k + 2] + sp[p][4 * k + 3]);
;                 ip[16 * ct + 2 * kk + hi] = e4 + (hi ? xk : prev);
;                 prev = xk; asm volatile("" : "+v"(prev)); }
;             if (ct == 0) xcross = prev;
.LBB0_763:
	v_exp_f32_e32 v34, v89
	v_exp_f32_e32 v35, v35
	v_exp_f32_e32 v36, v88
	v_exp_f32_e32 v37, v96
	v_exp_f32_e32 v38, v86
	v_exp_f32_e32 v39, v97
	v_add_f32_e32 v40, 0, v34
	v_add_f32_e32 v41, 0, v35
	v_exp_f32_e32 v42, v87
	v_add_f32_e32 v40, v36, v40
	v_add_f32_e32 v41, v37, v41
	v_exp_f32_e32 v44, v85
	v_pk_add_f32 v[160:161], v[38:39], v[40:41]
	v_exp_f32_e32 v40, v84
	v_exp_f32_e32 v45, v58
	v_exp_f32_e32 v46, v82
	v_exp_f32_e32 v58, v83
	ds_read_b64_tr_b16 v[82:83], v238 offset:24576
	ds_read_b64_tr_b16 v[84:85], v238 offset:25088
	v_cvt_pk_bf16_f32 v86, v34, v36
	v_cvt_pk_bf16_f32 v87, v38, v42
	v_cvt_pk_bf16_f32 v88, v40, v44
	v_cvt_pk_bf16_f32 v89, v46, v58
	v_exp_f32_e32 v43, v94
	v_exp_f32_e32 v41, v95
	s_waitcnt lgkmcnt(0)
	v_mfma_f32_32x32x16_bf16 v[2:17], v[82:85], v[86:89], v[2:17]
	v_exp_f32_e32 v47, v93
	v_exp_f32_e32 v48, v56
	v_exp_f32_e32 v49, v62
	v_exp_f32_e32 v56, v57
	v_exp_f32_e32 v57, v60
	v_exp_f32_e32 v60, v54
	v_exp_f32_e32 v62, v55
	v_exp_f32_e32 v54, v52
	v_exp_f32_e32 v55, v92
	v_exp_f32_e32 v52, v53
	v_exp_f32_e32 v50, v50
	ds_read_b64_tr_b16 v[92:93], v238 offset:25600
	ds_read_b64_tr_b16 v[94:95], v238 offset:26112
	v_exp_f32_e32 v162, v51
	v_cvt_pk_bf16_f32 v82, v48, v56
	v_cvt_pk_bf16_f32 v83, v60, v62
	v_cvt_pk_bf16_f32 v84, v54, v52
	v_cvt_pk_bf16_f32 v85, v50, v162
	v_exp_f32_e32 v59, v59
	ds_read_b64_tr_b16 v[152:153], v238 offset:26624
	ds_read_b64_tr_b16 v[154:155], v238 offset:27136
	s_waitcnt lgkmcnt(2)
	v_mfma_f32_32x32x16_bf16 v[2:17], v[92:95], v[82:85], v[2:17]
	v_exp_f32_e32 v53, v91
	v_exp_f32_e32 v51, v90
	v_cvt_pk_bf16_f32 v90, v35, v37
	v_cvt_pk_bf16_f32 v91, v39, v43
	v_cvt_pk_bf16_f32 v92, v41, v45
	v_cvt_pk_bf16_f32 v93, v47, v59
	v_exp_f32_e32 v61, v61
	v_exp_f32_e32 v63, v63
	s_waitcnt lgkmcnt(0)
	v_mfma_f32_32x32x16_bf16 v[2:17], v[152:155], v[90:93], v[2:17]
	ds_read_b64_tr_b16 v[94:95], v238 offset:27648
	ds_read_b64_tr_b16 v[96:97], v238 offset:28160
	v_exp_f32_e32 v163, v65
	ds_read_b64_tr_b16 v[156:157], v238 offset:28672
	ds_read_b64_tr_b16 v[158:159], v238 offset:29184
	v_cvt_pk_bf16_f32 v152, v49, v57
	v_cvt_pk_bf16_f32 v153, v61, v63
	v_cvt_pk_bf16_f32 v154, v55, v53
	v_cvt_pk_bf16_f32 v155, v51, v163
	s_waitcnt lgkmcnt(0)
	v_mfma_f32_32x32x16_bf16 v[18:33], v[156:159], v[86:89], v[18:33]
	v_add_f32_e32 v34, v34, v36
	v_add_f32_e32 v36, v38, v42
	v_add_f32_e32 v34, v34, v36
	v_add_f32_e32 v38, v46, v58
	v_add_f32_e32 v35, v35, v37
	v_add_f32_e32 v37, v39, v43
	v_add_f32_e32 v35, v35, v37
	v_mfma_f32_32x32x16_bf16 v[2:17], v[94:97], v[152:155], v[2:17]
	v_add_f32_e64 v94, v42, v160
	v_add_f32_e64 v95, v43, v161
	v_add_f32_e32 v37, v47, v59
	v_add_f32_e64 v94, v40, v94
	v_add_f32_e64 v95, v41, v95
	s_mov_b64 s[10:11], s[42:43]
	v_add_f32_e32 v94, v44, v94
	v_add_f32_e32 v95, v45, v95
	v_add_f32_e32 v94, v46, v94
	v_add_f32_e32 v95, v47, v95
	s_nop 0
	v_pk_add_f32 v[160:161], v[58:59], v[94:95]
	ds_read_b64_tr_b16 v[94:95], v238 offset:29696
	ds_read_b64_tr_b16 v[96:97], v238 offset:30208
	v_pk_add_f32 v[86:87], v[48:49], v[160:161]
	s_waitcnt lgkmcnt(0)
	v_mfma_f32_32x32x16_bf16 v[18:33], v[94:97], v[82:85], v[18:33]
	v_add_f32_e64 v86, v56, v86
	v_add_f32_e64 v87, v57, v87
	v_add_f32_e64 v86, v60, v86
	v_add_f32_e64 v87, v61, v87
	v_add_f32_e64 v86, v62, v86
	v_add_f32_e64 v87, v63, v87
	v_pk_add_f32 v[156:157], v[54:55], v[86:87]
	ds_read_b64_tr_b16 v[86:87], v238 offset:30720
	ds_read_b64_tr_b16 v[88:89], v238 offset:31232
	v_pk_add_f32 v[82:83], v[52:53], v[156:157]
	s_waitcnt lgkmcnt(0)
	v_mfma_f32_32x32x16_bf16 v[18:33], v[86:89], v[90:93], v[18:33]
	v_add_f32_e64 v82, v50, v82
	v_add_f32_e64 v83, v51, v83
	v_and_b32_e32 v86, 64, v239
	v_add_f32_e64 v82, v162, v82
	v_add_f32_e64 v83, v163, v83
	v_add_u32_e32 v86, 64, v86
	v_add_f32_e32 v65, v82, v83
	v_add_f32_e32 v149, v149, v65
	v_xor_b32_e32 v65, 32, v239
	v_cmp_lt_i32_e32 vcc, v65, v86
	ds_read_b64_tr_b16 v[82:83], v238 offset:31744
	ds_read_b64_tr_b16 v[84:85], v238 offset:32256
	v_cndmask_b32_e32 v65, v239, v65, vcc
	v_lshlrev_b32_e32 v65, 2, v65
	ds_bpermute_b32 v86, v65, v42
	s_waitcnt lgkmcnt(1)
	v_mfma_f32_32x32x16_bf16 v[18:33], v[82:85], v[152:155], v[18:33]
	s_waitcnt lgkmcnt(0)
	v_cndmask_b32_e64 v36, v86, 0, s[42:43]
	v_add_f32_e32 v34, v34, v36
	ds_write_b32 v145, v34 offset:64
	ds_bpermute_b32 v34, v65, v58
	v_add_f32_e32 v36, v40, v44
	v_add_f32_e32 v36, v36, v38
	v_add_f32_e32 v40, v60, v62
	s_waitcnt lgkmcnt(0)
	v_cndmask_b32_e64 v38, v34, v86, s[42:43]
	v_add_f32_e32 v36, v36, v38
	ds_write_b32 v145, v36 offset:72
	ds_bpermute_b32 v36, v65, v62
	v_add_f32_e32 v38, v48, v56
	v_add_f32_e32 v38, v38, v40
	v_add_f32_e32 v40, v50, v162
	s_waitcnt lgkmcnt(0)
	v_cndmask_b32_e64 v34, v36, v34, s[42:43]
	v_add_f32_e32 v34, v38, v34
	ds_write_b32 v145, v34 offset:80
	ds_bpermute_b32 v34, v65, v162
	v_add_f32_e32 v38, v54, v52
	v_add_f32_e32 v38, v38, v40
	s_waitcnt lgkmcnt(0)
	v_cndmask_b32_e64 v36, v34, v36, s[42:43]
	v_add_f32_e32 v36, v38, v36
	ds_write_b32 v145, v36 offset:88
	ds_bpermute_b32 v36, v65, v43
	s_waitcnt lgkmcnt(0)
	v_cndmask_b32_e64 v34, v36, v34, s[42:43]
	v_add_f32_e32 v34, v35, v34
	ds_write_b32 v145, v34 offset:96
	ds_bpermute_b32 v34, v65, v59
	v_add_f32_e32 v35, v41, v45
	v_add_f32_e32 v35, v35, v37
	v_add_f32_e32 v37, v61, v63
	s_waitcnt lgkmcnt(0)
	v_cndmask_b32_e64 v36, v34, v36, s[42:43]
	v_add_f32_e32 v35, v35, v36
	ds_write_b32 v145, v35 offset:104
	ds_bpermute_b32 v35, v65, v63
	v_add_f32_e32 v36, v49, v57
	v_add_f32_e32 v36, v36, v37
	v_add_f32_e32 v37, v51, v163
	s_waitcnt lgkmcnt(0)
	v_cndmask_b32_e64 v34, v35, v34, s[42:43]
	v_add_f32_e32 v34, v36, v34
	ds_write_b32 v145, v34 offset:112
	ds_bpermute_b32 v34, v65, v163
	v_add_f32_e32 v36, v55, v53
	v_add_f32_e32 v36, v36, v37
	s_waitcnt lgkmcnt(0)
	v_cndmask_b32_e64 v35, v34, v35, s[42:43]
	v_add_f32_e32 v35, v36, v35
	ds_write_b32 v145, v35 offset:120
